# Res K-loop A-operand LDS-DMA loads marked nt (read-once stream; keeps hb resident for the next phase)
# baseline (speedup 1.0000x reference)
; #define PG8_STAGE(bufoff, gbase, voff) do { _Pragma("unroll") for (int _i = 0; _i < 2; ++_i) \
;         __builtin_amdgcn_global_load_lds((const unsigned*)((const char*)(gbase) + (voff)[_i]), (LAS unsigned*)(lds + (bufoff) + ldsw + _i * 8192), 16, 0, 0); } while (0)
; #define PG8_LDA(dst, b, h) do { _Pragma("unroll") for (int m = 0; m < 4; ++m) _Pragma("unroll") for (int k = 0; k < 2; ++k) dst[m][k] = *(const LAS bf16x8*)(lds + PG8_SA(b, h) + aoff + m * 2048 + k * 1024); } while (0)
; #define PG8_LDB(dst, b, h) do { _Pragma("unroll") for (int n = 0; n < 2; ++n) _Pragma("unroll") for (int k = 0; k < 2; ++k) dst[n][k] = *(const LAS bf16x8*)(lds + PG8_SB(b, h) + boff + n * 2048 + k * 1024); } while (0)
; #define PG8_MMA(ai, bj, At, Bt) do { __builtin_amdgcn_s_setprio(1); _Pragma("unroll") for (int m = 0; m < 4; ++m) _Pragma("unroll") for (int n = 0; n < 2; ++n) _Pragma("unroll") for (int k = 0; k < 2; ++k) \
;         acc[ai][bj][m][n] = MFMA16(Bt[n][k], At[m][k], acc[ai][bj][m][n]); __builtin_amdgcn_s_setprio(0); } while (0)
; #define PG8_WAIT_V(n) asm volatile("s_waitcnt vmcnt(" #n ")" ::: "memory")
; #define PG8_WAIT_L(n) asm volatile("s_waitcnt lgkmcnt(" #n ")" ::: "memory")
; #define PG8_BAR __builtin_amdgcn_s_barrier()
; #define PG8_SCHED __builtin_amdgcn_sched_barrier(0)
; template <class Epi>
; __device__ __forceinline__ void gemm_phase(LAS unsigned char* lds, const Gemm g, const StaticOrder& S, const Epi& E, int tid_) {
;     ...
;         for (int t = 0; t < nt; t += 2) {
;             const bool last = (t == nt - 2);
;             const char* a1 = cA + (size_t)(t + 1) * kstep;
;             const char* a2 = last ? nA : cA + (size_t)(t + 2) * kstep; const char* b2 = last ? nB : cB + (size_t)(t + 2) * kstep;
;             const char* a3 = a2 + kstep; const char* b3 = b2 + kstep;
;             PG8_LDB(B0, 0, 0); PG8_LDB(B1, 0, 1); PG8_SCHED; PG8_LDA(At, 0, 0); PG8_STAGE(PG8_SA(1, 1), a1 + hsA, voffA);
;             PG8_WAIT_V(8); PG8_WAIT_L(0); PG8_BAR; PG8_MMA(0, 0, At, B0); PG8_MMA(0, 1, At, B1); PG8_BAR; PG8_SCHED;
;             PG8_LDA(At, 0, 1); PG8_STAGE(PG8_SB(0, 0), b2, voffB); PG8_STAGE(PG8_SB(0, 1), b2 + hsB, voffB); PG8_STAGE(PG8_SA(0, 0), a2, voffA);
;             PG8_WAIT_V(8); PG8_WAIT_L(0); PG8_BAR; PG8_MMA(1, 0, At, B0); PG8_MMA(1, 1, At, B1); PG8_BAR; PG8_SCHED;
.LBB0_683:
	s_add_i32 s69, s54, 2
	s_add_u32 s70, s28, 0x80
	s_addc_u32 s55, s29, 0
	s_add_i32 s72, 0, 0x10000
	s_cmp_eq_u32 s63, s54
	s_cselect_b32 s55, s41, s55
	s_cselect_b32 s54, s40, s70
	s_cselect_b32 s71, s53, s23
	s_cselect_b32 s70, s52, s22
	s_add_i32 s73, 0, 0x14000
	v_add_u32_e32 v142, s72, v166
	v_add_u32_e32 v169, s73, v166
	ds_read_b128 v[130:133], v142
	ds_read_b128 v[134:137], v142 offset:1024
	ds_read_b128 v[138:141], v142 offset:2048
	ds_read_b128 v[142:145], v142 offset:3072
	ds_read_b128 v[146:149], v169
	ds_read_b128 v[150:153], v169 offset:1024
	ds_read_b128 v[170:173], v169 offset:2048
	ds_read_b128 v[174:177], v169 offset:3072
	v_lshl_add_u64 v[232:233], s[28:29], 0, v[162:163]
	s_add_i32 m0, s56, 0xc000
	ds_read_b128 v[178:181], v168
	ds_read_b128 v[198:201], v168 offset:1024
	ds_read_b128 v[202:205], v168 offset:2048
	ds_read_b128 v[206:209], v168 offset:3072
	ds_read_b128 v[216:219], v168 offset:4096
	ds_read_b128 v[220:223], v168 offset:5120
	ds_read_b128 v[224:227], v168 offset:6144
	ds_read_b128 v[228:231], v168 offset:7168
	global_load_lds_dwordx4 v[232:233], off nt
	v_lshl_add_u64 v[232:233], s[28:29], 0, v[164:165]
	s_add_i32 m0, s56, 0xe000
	s_nop 0
	global_load_lds_dwordx4 v[232:233], off nt
	s_waitcnt vmcnt(8)
	s_waitcnt lgkmcnt(0)
	s_barrier
	s_setprio 1
	s_waitcnt lgkmcnt(0)
	v_mfma_f32_16x16x32_bf16 v[126:129], v[130:133], v[178:181], v[126:129]
	v_mfma_f32_16x16x32_bf16 v[122:125], v[138:141], v[178:181], v[122:125]
	v_mfma_f32_16x16x32_bf16 v[110:113], v[130:133], v[202:205], v[110:113]
	v_mfma_f32_16x16x32_bf16 v[106:109], v[138:141], v[202:205], v[106:109]
	v_mfma_f32_16x16x32_bf16 v[94:97], v[130:133], v[216:219], v[94:97]
	v_mfma_f32_16x16x32_bf16 v[90:93], v[138:141], v[216:219], v[90:93]
	v_mfma_f32_16x16x32_bf16 v[76:79], v[130:133], v[224:227], v[76:79]
	v_mfma_f32_16x16x32_bf16 v[72:75], v[138:141], v[224:227], v[72:75]
	v_mfma_f32_16x16x32_bf16 v[126:129], v[134:137], v[198:201], v[126:129]
	v_mfma_f32_16x16x32_bf16 v[122:125], v[142:145], v[198:201], v[122:125]
	v_mfma_f32_16x16x32_bf16 v[110:113], v[134:137], v[206:209], v[110:113]
	v_mfma_f32_16x16x32_bf16 v[106:109], v[142:145], v[206:209], v[106:109]
	v_mfma_f32_16x16x32_bf16 v[94:97], v[134:137], v[220:223], v[94:97]
	v_mfma_f32_16x16x32_bf16 v[90:93], v[142:145], v[220:223], v[90:93]
	v_mfma_f32_16x16x32_bf16 v[76:79], v[134:137], v[228:231], v[76:79]
	v_mfma_f32_16x16x32_bf16 v[72:75], v[142:145], v[228:231], v[72:75]
	s_setprio 0
	s_setprio 1
	v_mfma_f32_16x16x32_bf16 v[118:121], v[146:149], v[178:181], v[118:121]
	v_mfma_f32_16x16x32_bf16 v[114:117], v[170:173], v[178:181], v[114:117]
	v_mfma_f32_16x16x32_bf16 v[102:105], v[146:149], v[202:205], v[102:105]
	v_mfma_f32_16x16x32_bf16 v[98:101], v[170:173], v[202:205], v[98:101]
	v_mfma_f32_16x16x32_bf16 v[86:89], v[146:149], v[216:219], v[86:89]
	v_mfma_f32_16x16x32_bf16 v[82:85], v[170:173], v[216:219], v[82:85]
	v_mfma_f32_16x16x32_bf16 v[68:71], v[146:149], v[224:227], v[68:71]
	v_mfma_f32_16x16x32_bf16 v[64:67], v[170:173], v[224:227], v[64:67]
	v_mfma_f32_16x16x32_bf16 v[118:121], v[150:153], v[198:201], v[118:121]
	v_mfma_f32_16x16x32_bf16 v[114:117], v[174:177], v[198:201], v[114:117]
	v_mfma_f32_16x16x32_bf16 v[102:105], v[150:153], v[206:209], v[102:105]
	v_mfma_f32_16x16x32_bf16 v[98:101], v[174:177], v[206:209], v[98:101]
	v_mfma_f32_16x16x32_bf16 v[86:89], v[150:153], v[220:223], v[86:89]
	v_mfma_f32_16x16x32_bf16 v[82:85], v[174:177], v[220:223], v[82:85]
	v_mfma_f32_16x16x32_bf16 v[68:71], v[150:153], v[228:231], v[68:71]
	v_mfma_f32_16x16x32_bf16 v[64:67], v[174:177], v[228:231], v[64:67]
	s_setprio 0
	s_barrier
	s_add_i32 s72, s72, s31
	v_lshl_add_u64 v[232:233], s[70:71], 0, v[156:157]
	s_mov_b32 m0, s72
	ds_read_b128 v[178:181], v168 offset:16384
	ds_read_b128 v[198:201], v168 offset:17408
	ds_read_b128 v[202:205], v168 offset:18432
	ds_read_b128 v[206:209], v168 offset:19456
	ds_read_b128 v[216:219], v168 offset:20480
	ds_read_b128 v[220:223], v168 offset:21504
	ds_read_b128 v[224:227], v168 offset:22528
	ds_read_b128 v[228:231], v168 offset:23552
	global_load_lds_dwordx4 v[232:233], off
	s_add_i32 m0, s72, 0x2000
	v_lshl_add_u64 v[234:235], s[70:71], 0, v[160:161]
	s_add_u32 s70, s70, s4
	s_addc_u32 s71, s71, 0
	s_add_i32 s72, s73, s31
	global_load_lds_dwordx4 v[234:235], off
	v_lshl_add_u64 v[236:237], s[70:71], 0, v[156:157]
	s_mov_b32 m0, s72
	v_lshl_add_u64 v[238:239], s[70:71], 0, v[160:161]
	global_load_lds_dwordx4 v[236:237], off
	s_add_i32 m0, s72, 0x2000
	v_lshl_add_u64 v[240:241], s[54:55], 0, v[154:155]
	global_load_lds_dwordx4 v[238:239], off
	s_mov_b32 m0, s56
	v_lshl_add_u64 v[242:243], s[54:55], 0, v[158:159]
	global_load_lds_dwordx4 v[240:241], off nt
	s_mov_b32 m0, s57
	s_nop 0
	global_load_lds_dwordx4 v[242:243], off nt
	s_waitcnt vmcnt(8)
	s_waitcnt lgkmcnt(0)
	s_barrier
; #define PG8_STAGE(bufoff, gbase, voff) do { _Pragma("unroll") for (int _i = 0; _i < 2; ++_i) \
;         __builtin_amdgcn_global_load_lds((const unsigned*)((const char*)(gbase) + (voff)[_i]), (LAS unsigned*)(lds + (bufoff) + ldsw + _i * 8192), 16, 0, 0); } while (0)
; #define PG8_LDA(dst, b, h) do { _Pragma("unroll") for (int m = 0; m < 4; ++m) _Pragma("unroll") for (int k = 0; k < 2; ++k) dst[m][k] = *(const LAS bf16x8*)(lds + PG8_SA(b, h) + aoff + m * 2048 + k * 1024); } while (0)
; #define PG8_LDB(dst, b, h) do { _Pragma("unroll") for (int n = 0; n < 2; ++n) _Pragma("unroll") for (int k = 0; k < 2; ++k) dst[n][k] = *(const LAS bf16x8*)(lds + PG8_SB(b, h) + boff + n * 2048 + k * 1024); } while (0)
; #define PG8_MMA(ai, bj, At, Bt) do { __builtin_amdgcn_s_setprio(1); _Pragma("unroll") for (int m = 0; m < 4; ++m) _Pragma("unroll") for (int n = 0; n < 2; ++n) _Pragma("unroll") for (int k = 0; k < 2; ++k) \
;         acc[ai][bj][m][n] = MFMA16(Bt[n][k], At[m][k], acc[ai][bj][m][n]); __builtin_amdgcn_s_setprio(0); } while (0)
; #define PG8_WAIT_V(n) asm volatile("s_waitcnt vmcnt(" #n ")" ::: "memory")
; #define PG8_WAIT_L(n) asm volatile("s_waitcnt lgkmcnt(" #n ")" ::: "memory")
; #define PG8_BAR __builtin_amdgcn_s_barrier()
; #define PG8_SCHED __builtin_amdgcn_sched_barrier(0)
; template <class Epi>
; __device__ __forceinline__ void gemm_phase(LAS unsigned char* lds, const Gemm g, const StaticOrder& S, const Epi& E, int tid_) {
;     ...
;             PG8_WAIT_V(8); PG8_WAIT_L(0); PG8_BAR; PG8_MMA(1, 0, At, B0); PG8_MMA(1, 1, At, B1); PG8_BAR; PG8_SCHED;
;             PG8_LDB(B0, 1, 0); PG8_LDB(B1, 1, 1); PG8_SCHED; PG8_LDA(At, 1, 0); PG8_STAGE(PG8_SA(0, 1), a2 + hsA, voffA);
;             PG8_WAIT_V(8); PG8_WAIT_L(0); PG8_BAR; PG8_MMA(0, 0, At, B0); PG8_MMA(0, 1, At, B1); PG8_BAR; PG8_SCHED;
;             PG8_LDA(At, 1, 1); PG8_STAGE(PG8_SB(1, 0), b3, voffB); PG8_STAGE(PG8_SB(1, 1), b3 + hsB, voffB); PG8_STAGE(PG8_SA(1, 0), a3, voffA);
	s_setprio 1
	s_waitcnt lgkmcnt(0)
	v_mfma_f32_16x16x32_bf16 v[60:63], v[130:133], v[178:181], v[60:63]
	v_mfma_f32_16x16x32_bf16 v[56:59], v[138:141], v[178:181], v[56:59]
	v_mfma_f32_16x16x32_bf16 v[44:47], v[130:133], v[202:205], v[44:47]
	v_mfma_f32_16x16x32_bf16 v[40:43], v[138:141], v[202:205], v[40:43]
	v_mfma_f32_16x16x32_bf16 v[28:31], v[130:133], v[216:219], v[28:31]
	v_mfma_f32_16x16x32_bf16 v[24:27], v[138:141], v[216:219], v[24:27]
	v_mfma_f32_16x16x32_bf16 v[12:15], v[130:133], v[224:227], v[12:15]
	v_mfma_f32_16x16x32_bf16 v[8:11], v[138:141], v[224:227], v[8:11]
	v_mfma_f32_16x16x32_bf16 v[60:63], v[134:137], v[198:201], v[60:63]
	v_mfma_f32_16x16x32_bf16 v[56:59], v[142:145], v[198:201], v[56:59]
	v_mfma_f32_16x16x32_bf16 v[44:47], v[134:137], v[206:209], v[44:47]
	v_mfma_f32_16x16x32_bf16 v[40:43], v[142:145], v[206:209], v[40:43]
	v_mfma_f32_16x16x32_bf16 v[28:31], v[134:137], v[220:223], v[28:31]
	v_mfma_f32_16x16x32_bf16 v[24:27], v[142:145], v[220:223], v[24:27]
	v_mfma_f32_16x16x32_bf16 v[12:15], v[134:137], v[228:231], v[12:15]
	v_mfma_f32_16x16x32_bf16 v[8:11], v[142:145], v[228:231], v[8:11]
	s_setprio 0
	s_setprio 1
	v_mfma_f32_16x16x32_bf16 v[52:55], v[146:149], v[178:181], v[52:55]
	v_mfma_f32_16x16x32_bf16 v[48:51], v[170:173], v[178:181], v[48:51]
	v_mfma_f32_16x16x32_bf16 v[36:39], v[146:149], v[202:205], v[36:39]
	v_mfma_f32_16x16x32_bf16 v[32:35], v[170:173], v[202:205], v[32:35]
	v_mfma_f32_16x16x32_bf16 v[20:23], v[146:149], v[216:219], v[20:23]
	v_mfma_f32_16x16x32_bf16 v[16:19], v[170:173], v[216:219], v[16:19]
	v_mfma_f32_16x16x32_bf16 v[4:7], v[146:149], v[224:227], v[4:7]
	v_mfma_f32_16x16x32_bf16 v[0:3], v[170:173], v[224:227], v[0:3]
	v_mfma_f32_16x16x32_bf16 v[52:55], v[150:153], v[198:201], v[52:55]
	v_mfma_f32_16x16x32_bf16 v[48:51], v[174:177], v[198:201], v[48:51]
	v_mfma_f32_16x16x32_bf16 v[36:39], v[150:153], v[206:209], v[36:39]
	v_mfma_f32_16x16x32_bf16 v[32:35], v[174:177], v[206:209], v[32:35]
	v_mfma_f32_16x16x32_bf16 v[20:23], v[150:153], v[220:223], v[20:23]
	v_mfma_f32_16x16x32_bf16 v[16:19], v[174:177], v[220:223], v[16:19]
	v_mfma_f32_16x16x32_bf16 v[4:7], v[150:153], v[228:231], v[4:7]
	v_mfma_f32_16x16x32_bf16 v[0:3], v[174:177], v[228:231], v[0:3]
	s_setprio 0
	s_barrier
	s_add_i32 s70, 0, 0x18000
	s_add_i32 s71, 0, 0x1c000
	v_add_u32_e32 v142, s70, v166
	v_add_u32_e32 v169, s71, v166
	ds_read_b128 v[130:133], v142
	ds_read_b128 v[134:137], v142 offset:1024
	ds_read_b128 v[138:141], v142 offset:2048
	ds_read_b128 v[142:145], v142 offset:3072
	ds_read_b128 v[146:149], v169
	ds_read_b128 v[150:153], v169 offset:1024
	ds_read_b128 v[170:173], v169 offset:2048
	ds_read_b128 v[174:177], v169 offset:3072
	s_add_u32 s54, s54, s4
	s_addc_u32 s55, s55, 0
	s_mov_b32 m0, s58
	v_lshl_add_u64 v[244:245], s[54:55], 0, v[154:155]
	ds_read_b128 v[178:181], v168 offset:32768
	ds_read_b128 v[198:201], v168 offset:33792
	ds_read_b128 v[202:205], v168 offset:34816
	ds_read_b128 v[206:209], v168 offset:35840
	ds_read_b128 v[216:219], v168 offset:36864
	ds_read_b128 v[220:223], v168 offset:37888
	ds_read_b128 v[224:227], v168 offset:38912
	ds_read_b128 v[228:231], v168 offset:39936
	global_load_lds_dwordx4 v[244:245], off nt
	v_lshl_add_u64 v[244:245], s[54:55], 0, v[158:159]
	s_mov_b32 m0, s59
	s_nop 0
	global_load_lds_dwordx4 v[244:245], off nt
	s_waitcnt vmcnt(8)
	s_waitcnt lgkmcnt(0)
	s_barrier
	s_setprio 1
	s_waitcnt lgkmcnt(0)
	v_mfma_f32_16x16x32_bf16 v[126:129], v[130:133], v[178:181], v[126:129]
	v_mfma_f32_16x16x32_bf16 v[122:125], v[138:141], v[178:181], v[122:125]
	v_mfma_f32_16x16x32_bf16 v[110:113], v[130:133], v[202:205], v[110:113]
	v_mfma_f32_16x16x32_bf16 v[106:109], v[138:141], v[202:205], v[106:109]
	v_mfma_f32_16x16x32_bf16 v[94:97], v[130:133], v[216:219], v[94:97]
	v_mfma_f32_16x16x32_bf16 v[90:93], v[138:141], v[216:219], v[90:93]
	v_mfma_f32_16x16x32_bf16 v[76:79], v[130:133], v[224:227], v[76:79]
	v_mfma_f32_16x16x32_bf16 v[72:75], v[138:141], v[224:227], v[72:75]
	v_mfma_f32_16x16x32_bf16 v[126:129], v[134:137], v[198:201], v[126:129]
	v_mfma_f32_16x16x32_bf16 v[122:125], v[142:145], v[198:201], v[122:125]
	v_mfma_f32_16x16x32_bf16 v[110:113], v[134:137], v[206:209], v[110:113]
	v_mfma_f32_16x16x32_bf16 v[106:109], v[142:145], v[206:209], v[106:109]
	v_mfma_f32_16x16x32_bf16 v[94:97], v[134:137], v[220:223], v[94:97]
	v_mfma_f32_16x16x32_bf16 v[90:93], v[142:145], v[220:223], v[90:93]
	v_mfma_f32_16x16x32_bf16 v[76:79], v[134:137], v[228:231], v[76:79]
	v_mfma_f32_16x16x32_bf16 v[72:75], v[142:145], v[228:231], v[72:75]
	s_setprio 0
	s_setprio 1
	v_mfma_f32_16x16x32_bf16 v[118:121], v[146:149], v[178:181], v[118:121]
	v_mfma_f32_16x16x32_bf16 v[114:117], v[170:173], v[178:181], v[114:117]
	v_mfma_f32_16x16x32_bf16 v[102:105], v[146:149], v[202:205], v[102:105]
	v_mfma_f32_16x16x32_bf16 v[98:101], v[170:173], v[202:205], v[98:101]
	v_mfma_f32_16x16x32_bf16 v[86:89], v[146:149], v[216:219], v[86:89]
	v_mfma_f32_16x16x32_bf16 v[82:85], v[170:173], v[216:219], v[82:85]
	v_mfma_f32_16x16x32_bf16 v[68:71], v[146:149], v[224:227], v[68:71]
	v_mfma_f32_16x16x32_bf16 v[64:67], v[170:173], v[224:227], v[64:67]
	v_mfma_f32_16x16x32_bf16 v[118:121], v[150:153], v[198:201], v[118:121]
	v_mfma_f32_16x16x32_bf16 v[114:117], v[174:177], v[198:201], v[114:117]
	v_mfma_f32_16x16x32_bf16 v[102:105], v[150:153], v[206:209], v[102:105]
	v_mfma_f32_16x16x32_bf16 v[98:101], v[174:177], v[206:209], v[98:101]
	v_mfma_f32_16x16x32_bf16 v[86:89], v[150:153], v[220:223], v[86:89]
	v_mfma_f32_16x16x32_bf16 v[82:85], v[174:177], v[220:223], v[82:85]
	v_mfma_f32_16x16x32_bf16 v[68:71], v[150:153], v[228:231], v[68:71]
	v_mfma_f32_16x16x32_bf16 v[64:67], v[174:177], v[228:231], v[64:67]
	s_setprio 0
	s_barrier
; #define PG8_STAGE(bufoff, gbase, voff) do { _Pragma("unroll") for (int _i = 0; _i < 2; ++_i) \
;         __builtin_amdgcn_global_load_lds((const unsigned*)((const char*)(gbase) + (voff)[_i]), (LAS unsigned*)(lds + (bufoff) + ldsw + _i * 8192), 16, 0, 0); } while (0)
; #define PG8_LDA(dst, b, h) do { _Pragma("unroll") for (int m = 0; m < 4; ++m) _Pragma("unroll") for (int k = 0; k < 2; ++k) dst[m][k] = *(const LAS bf16x8*)(lds + PG8_SA(b, h) + aoff + m * 2048 + k * 1024); } while (0)
; #define PG8_MMA(ai, bj, At, Bt) do { __builtin_amdgcn_s_setprio(1); _Pragma("unroll") for (int m = 0; m < 4; ++m) _Pragma("unroll") for (int n = 0; n < 2; ++n) _Pragma("unroll") for (int k = 0; k < 2; ++k) \
;         acc[ai][bj][m][n] = MFMA16(Bt[n][k], At[m][k], acc[ai][bj][m][n]); __builtin_amdgcn_s_setprio(0); } while (0)
; #define PG8_WAIT_V(n) asm volatile("s_waitcnt vmcnt(" #n ")" ::: "memory")
; #define PG8_WAIT_L(n) asm volatile("s_waitcnt lgkmcnt(" #n ")" ::: "memory")
; #define PG8_BAR __builtin_amdgcn_s_barrier()
; #define PG8_SCHED __builtin_amdgcn_sched_barrier(0)
; template <class Epi>
; __device__ __forceinline__ void gemm_phase(LAS unsigned char* lds, const Gemm g, const StaticOrder& S, const Epi& E, int tid_) {
;     ...
;             PG8_LDA(At, 1, 1); PG8_STAGE(PG8_SB(1, 0), b3, voffB); PG8_STAGE(PG8_SB(1, 1), b3 + hsB, voffB); PG8_STAGE(PG8_SA(1, 0), a3, voffA);
;             PG8_WAIT_V(8); PG8_WAIT_L(0); PG8_BAR; PG8_MMA(1, 0, At, B0); PG8_MMA(1, 1, At, B1); PG8_BAR; PG8_SCHED;
;         }
	s_add_i32 s54, s70, s31
	v_lshl_add_u64 v[232:233], v[232:233], 0, s[6:7]
	s_mov_b32 m0, s54
	ds_read_b128 v[178:181], v168 offset:49152
	ds_read_b128 v[198:201], v168 offset:50176
	ds_read_b128 v[202:205], v168 offset:51200
	ds_read_b128 v[206:209], v168 offset:52224
	ds_read_b128 v[216:219], v168 offset:53248
	ds_read_b128 v[220:223], v168 offset:54272
	ds_read_b128 v[224:227], v168 offset:55296
	ds_read_b128 v[228:231], v168 offset:56320
	global_load_lds_dwordx4 v[232:233], off
	v_lshl_add_u64 v[232:233], v[234:235], 0, s[6:7]
	s_add_i32 m0, s54, 0x2000
	s_add_i32 s54, s71, s31
	global_load_lds_dwordx4 v[232:233], off
	v_lshl_add_u64 v[232:233], v[236:237], 0, s[6:7]
	s_mov_b32 m0, s54
	s_nop 0
	global_load_lds_dwordx4 v[232:233], off
	v_lshl_add_u64 v[232:233], v[238:239], 0, s[6:7]
	s_add_i32 m0, s54, 0x2000
	s_nop 0
	global_load_lds_dwordx4 v[232:233], off
	v_lshl_add_u64 v[232:233], v[240:241], 0, s[6:7]
	s_mov_b32 m0, s60
	s_nop 0
	global_load_lds_dwordx4 v[232:233], off nt
	v_lshl_add_u64 v[232:233], v[242:243], 0, s[6:7]
	s_mov_b32 m0, s61
	s_nop 0
	global_load_lds_dwordx4 v[232:233], off nt
	s_waitcnt vmcnt(8)
	s_waitcnt lgkmcnt(0)
	s_barrier
	s_setprio 1
	s_waitcnt lgkmcnt(0)
	v_mfma_f32_16x16x32_bf16 v[60:63], v[130:133], v[178:181], v[60:63]
	v_mfma_f32_16x16x32_bf16 v[56:59], v[138:141], v[178:181], v[56:59]
	v_mfma_f32_16x16x32_bf16 v[44:47], v[130:133], v[202:205], v[44:47]
	v_mfma_f32_16x16x32_bf16 v[40:43], v[138:141], v[202:205], v[40:43]
	v_mfma_f32_16x16x32_bf16 v[28:31], v[130:133], v[216:219], v[28:31]
	v_mfma_f32_16x16x32_bf16 v[24:27], v[138:141], v[216:219], v[24:27]
	v_mfma_f32_16x16x32_bf16 v[12:15], v[130:133], v[224:227], v[12:15]
	v_mfma_f32_16x16x32_bf16 v[8:11], v[138:141], v[224:227], v[8:11]
	v_mfma_f32_16x16x32_bf16 v[60:63], v[134:137], v[198:201], v[60:63]
	v_mfma_f32_16x16x32_bf16 v[56:59], v[142:145], v[198:201], v[56:59]
	v_mfma_f32_16x16x32_bf16 v[44:47], v[134:137], v[206:209], v[44:47]
	v_mfma_f32_16x16x32_bf16 v[40:43], v[142:145], v[206:209], v[40:43]
	v_mfma_f32_16x16x32_bf16 v[28:31], v[134:137], v[220:223], v[28:31]
	v_mfma_f32_16x16x32_bf16 v[24:27], v[142:145], v[220:223], v[24:27]
	v_mfma_f32_16x16x32_bf16 v[12:15], v[134:137], v[228:231], v[12:15]
	v_mfma_f32_16x16x32_bf16 v[8:11], v[142:145], v[228:231], v[8:11]
	s_setprio 0
	s_setprio 1
	v_mfma_f32_16x16x32_bf16 v[52:55], v[146:149], v[178:181], v[52:55]
	v_mfma_f32_16x16x32_bf16 v[48:51], v[170:173], v[178:181], v[48:51]
	v_mfma_f32_16x16x32_bf16 v[36:39], v[146:149], v[202:205], v[36:39]
	v_mfma_f32_16x16x32_bf16 v[32:35], v[170:173], v[202:205], v[32:35]
	v_mfma_f32_16x16x32_bf16 v[20:23], v[146:149], v[216:219], v[20:23]
	v_mfma_f32_16x16x32_bf16 v[16:19], v[170:173], v[216:219], v[16:19]
	v_mfma_f32_16x16x32_bf16 v[4:7], v[146:149], v[224:227], v[4:7]
	v_mfma_f32_16x16x32_bf16 v[0:3], v[170:173], v[224:227], v[0:3]
	v_mfma_f32_16x16x32_bf16 v[52:55], v[150:153], v[198:201], v[52:55]
	v_mfma_f32_16x16x32_bf16 v[48:51], v[174:177], v[198:201], v[48:51]
	v_mfma_f32_16x16x32_bf16 v[36:39], v[150:153], v[206:209], v[36:39]
	v_mfma_f32_16x16x32_bf16 v[32:35], v[174:177], v[206:209], v[32:35]
	v_mfma_f32_16x16x32_bf16 v[20:23], v[150:153], v[220:223], v[20:23]
	v_mfma_f32_16x16x32_bf16 v[16:19], v[174:177], v[220:223], v[16:19]
	v_mfma_f32_16x16x32_bf16 v[4:7], v[150:153], v[228:231], v[4:7]
	v_mfma_f32_16x16x32_bf16 v[0:3], v[174:177], v[228:231], v[0:3]
	s_setprio 0
	s_barrier
	s_add_u32 s28, s28, 0x100
	s_addc_u32 s29, s29, 0
	s_add_u32 s22, s22, 0x100
	s_addc_u32 s23, s23, 0
	s_cmp_ge_i32 s69, s1
	s_mov_b32 s54, s69
	s_cbranch_scc0 .LBB0_683
	s_and_b64 vcc, exec, s[50:51]
	s_cbranch_vccz .LBB0_686
